# w_in_transpose_loads_batched
# speedup vs baseline: 1.0470x; 1.0282x over previous
; #define LAS __attribute__((address_space(3)))
; __device__ __forceinline__ void p0_transpose_item(const float* W, int N, int ksrc0, int nsrc0, const float* ksc, bf16_t* WT, int nrow0, int kdst0, LAS float* scr, int lane) {
; #pragma unroll 8
;     for (int i = 0; i < 32; ++i) { const int kk = 2 * i + (lane >> 5); float v = W[(size_t)(ksrc0 + kk) * N + nsrc0 + (lane & 31)]; if (ksc) v *= ksc[ksrc0 + kk]; scr[kk * 33 + (lane & 31)] = v; }
;     asm volatile("s_waitcnt lgkmcnt(0)" ::: "memory");
.LBB0_90:
	s_and_b64 vcc, exec, s[10:11]
	s_cbranch_vccnz .Lwt_fast
	v_lshl_add_u64 v[42:43], v[40:41], 0, s[16:17]
	global_load_dword v21, v[42:43], off
	v_cndmask_b32_e64 v42, 0, 1, s[10:11]
	v_cmp_ne_u32_e64 s[0:1], 1, v42
	s_andn2_b64 vcc, exec, s[10:11]
	s_cbranch_vccnz .LBB0_92
	v_lshl_add_u64 v[42:43], s[18:19], 0, v[38:39]
	global_load_dword v42, v[42:43], off
	s_waitcnt vmcnt(0)
	v_mul_f32_e32 v21, v21, v42

; #define LAS __attribute__((address_space(3)))
; __device__ __forceinline__ void p0_transpose_item(const float* W, int N, int ksrc0, int nsrc0, const float* ksc, bf16_t* WT, int nrow0, int kdst0, LAS float* scr, int lane) {
; #pragma unroll 8
;     for (int i = 0; i < 32; ++i) { const int kk = 2 * i + (lane >> 5); float v = W[(size_t)(ksrc0 + kk) * N + nsrc0 + (lane & 31)]; if (ksc) v *= ksc[ksrc0 + kk]; scr[kk * 33 + (lane & 31)] = v; }
;     asm volatile("s_waitcnt lgkmcnt(0)" ::: "memory");
.Lwt_fast:
	v_lshl_add_u64 v[60:61], v[40:41], 0, s[16:17]
	global_load_dword v70, v[60:61], off
	v_lshl_add_u64 v[60:61], v[36:37], 0, s[16:17]
	global_load_dword v71, v[60:61], off
	v_lshl_add_u64 v[60:61], v[34:35], 0, s[16:17]
	global_load_dword v72, v[60:61], off
	v_lshl_add_u64 v[60:61], v[32:33], 0, s[16:17]
	global_load_dword v73, v[60:61], off
	v_lshl_add_u64 v[60:61], v[30:31], 0, s[16:17]
	global_load_dword v74, v[60:61], off
	v_lshl_add_u64 v[60:61], v[28:29], 0, s[16:17]
	global_load_dword v75, v[60:61], off
	v_lshl_add_u64 v[60:61], v[26:27], 0, s[16:17]
	global_load_dword v76, v[60:61], off
	v_lshl_add_u64 v[60:61], v[22:23], 0, s[16:17]
	global_load_dword v77, v[60:61], off
	v_lshl_add_u64 v[62:63], s[18:19], 0, v[38:39]
	global_load_dword v80, v[62:63], off
	v_lshl_add_u64 v[64:65], s[18:19], 0, v[24:25]
	global_load_dword v81, v[64:65], off offset:8
	global_load_dword v82, v[64:65], off offset:16
	global_load_dword v83, v[64:65], off offset:24
	global_load_dword v84, v[64:65], off offset:32
	global_load_dword v85, v[64:65], off offset:40
	global_load_dword v86, v[64:65], off offset:48
	global_load_dword v87, v[64:65], off offset:56
	s_waitcnt vmcnt(0)
	v_mul_f32_e32 v70, v70, v80
	v_mul_f32_e32 v71, v71, v81
	v_mul_f32_e32 v72, v72, v82
	v_mul_f32_e32 v73, v73, v83
	v_mul_f32_e32 v74, v74, v84
	v_mul_f32_e32 v75, v75, v85
	v_mul_f32_e32 v76, v76, v86
	v_mul_f32_e32 v77, v77, v87
	ds_write_b32 v2, v70
	ds_write_b32 v2, v71 offset:264
	ds_write_b32 v2, v72 offset:528
	ds_write_b32 v2, v73 offset:792
	ds_write_b32 v2, v74 offset:1056
	ds_write_b32 v2, v75 offset:1320
	ds_write_b32 v2, v76 offset:1584
	ds_write_b32 v2, v77 offset:1848
	s_add_u32 s16, s16, 0x54000
	s_addc_u32 s17, s17, 0
	s_add_u32 s18, s18, 64
	s_addc_u32 s19, s19, 0
	v_add_u32_e32 v2, 0x840, v2
	s_cmp_lg_u32 s16, 0x150000
	s_cbranch_scc1 .Lwt_fast
	s_branch .LBB0_44
